# cache policy: nontemporal hint on the 16 once-read gate loads of the branch epilogue
# speedup vs baseline: 1.0085x; 1.0024x over previous
.LBB0_114:
	s_lshl_b32 s22, s52, 4
	s_lshl_b32 s28, s26, 5
	s_add_i32 s22, s22, s20
	s_ashr_i32 s29, s28, 31
	s_lshl_b32 s27, s55, 3
	s_ashr_i32 s23, s22, 31
	s_ashr_i32 s30, s27, 31
	s_or_b64 s[28:29], s[28:29], s[0:1]
	s_add_u32 s28, s28, s27
	s_addc_u32 s29, s29, s30
	s_lshl_b64 s[22:23], s[22:23], 17
	s_lshl_b64 s[28:29], s[28:29], 10
	s_add_u32 s22, s78, s22
	s_addc_u32 s23, s79, s23
	s_add_u32 s22, s22, s28
	s_addc_u32 s23, s23, s29
	v_mov_b32_e32 v100, v245
	s_cmp_eq_u32 s26, 3
	s_cselect_b64 s[36:37], -1, 0
	v_ashrrev_i32_e32 v101, 31, v100
	v_lshl_add_u64 v[208:209], v[100:101], 4, s[22:23]
	s_and_b64 s[28:29], s[36:37], exec
	global_load_dwordx4 v[198:201], v[208:209], off nt
	s_cselect_b32 s27, 0, 0x800
	s_lshl_b32 s88, s27, 4
	v_lshl_add_u64 v[100:101], v[208:209], 0, s[88:89]
	global_load_dwordx4 v[202:205], v[100:101], off nt
	s_mov_b64 s[22:23], 0x20000
	v_lshl_add_u64 v[100:101], v[208:209], 0, s[22:23]
	s_mov_b32 s22, 0x21000
	v_add_co_u32_e32 v102, vcc, s22, v208
	v_lshl_add_u64 v[100:101], v[100:101], 0, s[88:89]
	s_nop 0
	v_addc_co_u32_e32 v103, vcc, 0, v209, vcc
	s_mov_b64 s[22:23], 0x40000
	global_load_dwordx4 v[180:183], v[102:103], off offset:-4096 nt
	global_load_dwordx4 v[176:179], v[100:101], off nt
	v_lshl_add_u64 v[100:101], v[208:209], 0, s[22:23]
	s_mov_b32 s22, 0x41000
	v_lshl_add_u64 v[100:101], v[100:101], 0, s[88:89]
	v_add_co_u32_e32 v104, vcc, s22, v208
	global_load_dwordx4 v[172:175], v[100:101], off nt
	global_load_dwordx4 v[140:143], v[102:103], off nt
	v_lshl_add_u64 v[100:101], v[208:209], 0, s[82:83]
	v_addc_co_u32_e32 v105, vcc, 0, v209, vcc
	v_lshl_add_u64 v[100:101], v[100:101], 0, s[88:89]
	global_load_dwordx4 v[168:171], v[104:105], off offset:-4096 nt
	global_load_dwordx4 v[160:163], v[100:101], off nt
	s_mov_b32 s22, 0x61000
	v_lshl_add_u64 v[100:101], v[208:209], 0, s[94:95]
	v_add_co_u32_e32 v106, vcc, s22, v208
	v_lshl_add_u64 v[100:101], v[100:101], 0, s[88:89]
	s_mov_b64 s[22:23], 0x21000
	global_load_dwordx4 v[152:155], v[100:101], off nt
	global_load_dwordx4 v[120:123], v[104:105], off nt
	v_lshl_add_u64 v[100:101], v[208:209], 0, s[22:23]
	v_addc_co_u32_e32 v107, vcc, 0, v209, vcc
	s_movk_i32 s4, 0x1000
	v_lshl_add_u64 v[100:101], v[100:101], 0, s[88:89]
	s_mov_b64 s[22:23], 0x41000
	global_load_dwordx4 v[164:167], v[106:107], off offset:-4096 nt
	global_load_dwordx4 v[132:135], v[100:101], off nt
	v_add_co_u32_e32 v116, vcc, s4, v208
	v_lshl_add_u64 v[100:101], v[208:209], 0, s[22:23]
	s_nop 0
	v_addc_co_u32_e32 v117, vcc, 0, v209, vcc
	v_lshl_add_u64 v[100:101], v[100:101], 0, s[88:89]
	s_mov_b64 s[22:23], 0x61000
	global_load_dwordx4 v[156:159], v[116:117], off nt
	s_movk_i32 s33, 0x3fff
	global_load_dwordx4 v[116:119], v[100:101], off nt
	s_cmp_lg_u32 s26, 3
	global_load_dwordx4 v[104:107], v[106:107], off nt
	v_lshl_add_u64 v[100:101], v[208:209], 0, s[22:23]
	v_lshl_add_u64 v[100:101], v[100:101], 0, s[88:89]
	global_load_dwordx4 v[100:103], v[100:101], off nt
	v_lshl_add_u32 v216, s52, 8, v242
	s_waitcnt vmcnt(14)
	v_lshlrev_b32_e32 v206, 16, v198
	v_and_b32_e32 v207, 0xffff0000, v198
	v_rcp_f32_e32 v206, v206
	v_rcp_f32_e32 v207, v207
	v_lshlrev_b32_e32 v210, 16, v199
	v_and_b32_e32 v211, 0xffff0000, v199
	v_lshlrev_b32_e32 v198, 16, v202
	v_and_b32_e32 v199, 0xffff0000, v202
	v_pk_mul_f32 v[198:199], v[206:207], v[198:199]
	v_lshlrev_b32_e32 v212, 16, v200
	v_cndmask_b32_e64 v199, v199, v207, s[36:37]
	v_cndmask_b32_e64 v198, v198, v206, s[36:37]
	v_pk_mul_f32 v[198:199], v[148:149], v[198:199]
	v_rcp_f32_e32 v148, v210
	v_rcp_f32_e32 v149, v211
	v_and_b32_e32 v213, 0xffff0000, v200
	v_lshlrev_b32_e32 v214, 16, v201
	v_and_b32_e32 v215, 0xffff0000, v201
	v_lshlrev_b32_e32 v200, 16, v203
	v_and_b32_e32 v201, 0xffff0000, v203
	v_pk_mul_f32 v[200:201], v[148:149], v[200:201]
	v_lshlrev_b32_e32 v202, 16, v204
	v_cndmask_b32_e64 v149, v201, v149, s[36:37]
	v_cndmask_b32_e64 v148, v200, v148, s[36:37]
	v_pk_mul_f32 v[200:201], v[150:151], v[148:149]
	v_rcp_f32_e32 v148, v212
	v_rcp_f32_e32 v149, v213
	v_and_b32_e32 v203, 0xffff0000, v204
	v_lshlrev_b32_e32 v204, 16, v205
	v_and_b32_e32 v205, 0xffff0000, v205
	v_pk_mul_f32 v[150:151], v[148:149], v[202:203]
	v_lshl_or_b32 v206, s55, 8, v192
	v_cndmask_b32_e64 v149, v151, v149, s[36:37]
	v_cndmask_b32_e64 v148, v150, v148, s[36:37]
	v_pk_mul_f32 v[202:203], v[144:145], v[148:149]
	v_rcp_f32_e32 v144, v214
	v_rcp_f32_e32 v145, v215
	s_nop 0
	v_pk_mul_f32 v[148:149], v[144:145], v[204:205]
	s_nop 0
	v_cndmask_b32_e64 v145, v149, v145, s[36:37]
	v_cndmask_b32_e64 v144, v148, v144, s[36:37]
	v_pk_mul_f32 v[204:205], v[146:147], v[144:145]
	s_cbranch_scc1 .LBB0_116
	v_ashrrev_i32_e32 v217, 31, v216
	s_nop 1
	v_lshlrev_b64 v[148:149], 11, v[216:217]
	v_readlane_b32 s6, v253, 18
	v_readlane_b32 s7, v253, 19
	v_ashrrev_i32_e32 v207, 31, v206
	v_cvt_pk_bf16_f32 v144, v198, v199
	v_cvt_pk_bf16_f32 v145, v200, v201
	v_cvt_pk_bf16_f32 v146, v202, v203
	v_cvt_pk_bf16_f32 v147, v204, v205
	s_nop 0
	v_lshl_add_u64 v[148:149], s[6:7], 0, v[148:149]
	v_lshl_add_u64 v[148:149], v[206:207], 1, v[148:149]
	s_nop 1
	global_store_dwordx4 v[148:149], v[144:147], off
